# P3 flat scan (63 loads up front) with sc1 on the RTB stores; on top of v126
# speedup vs baseline: 1.0002x; 1.0002x over previous
.LBB0_477:
	v_add_co_u32_e32 v6, vcc, 0xfff88000, v2
	s_nop 1
	v_addc_co_u32_e32 v7, vcc, -1, v3, vcc
	s_nop 0
	v_add_co_u32_e32 v14, vcc, 0xfbf88000, v2
	s_nop 1
	v_addc_co_u32_e32 v15, vcc, -1, v3, vcc
	global_load_dword v60, v[6:7], off nt
	v_add_co_u32_e32 v6, vcc, 0x8000, v6
	s_nop 1
	v_addc_co_u32_e32 v7, vcc, 0, v7, vcc
	global_load_dword v61, v[6:7], off nt
	v_add_co_u32_e32 v6, vcc, 0x8000, v6
	s_nop 1
	v_addc_co_u32_e32 v7, vcc, 0, v7, vcc
	global_load_dword v62, v[6:7], off nt
	v_add_co_u32_e32 v6, vcc, 0x8000, v6
	s_nop 1
	v_addc_co_u32_e32 v7, vcc, 0, v7, vcc
	global_load_dword v63, v[6:7], off nt
	v_add_co_u32_e32 v6, vcc, 0x8000, v6
	s_nop 1
	v_addc_co_u32_e32 v7, vcc, 0, v7, vcc
	global_load_dword v64, v[6:7], off nt
	v_add_co_u32_e32 v6, vcc, 0x8000, v6
	s_nop 1
	v_addc_co_u32_e32 v7, vcc, 0, v7, vcc
	global_load_dword v65, v[6:7], off nt
	v_add_co_u32_e32 v6, vcc, 0x8000, v6
	s_nop 1
	v_addc_co_u32_e32 v7, vcc, 0, v7, vcc
	global_load_dword v66, v[6:7], off nt
	v_add_co_u32_e32 v6, vcc, 0x8000, v6
	s_nop 1
	v_addc_co_u32_e32 v7, vcc, 0, v7, vcc
	global_load_dword v67, v[6:7], off nt
	v_add_co_u32_e32 v6, vcc, 0x8000, v6
	s_nop 1
	v_addc_co_u32_e32 v7, vcc, 0, v7, vcc
	global_load_dword v68, v[6:7], off nt
	v_add_co_u32_e32 v6, vcc, 0x8000, v6
	s_nop 1
	v_addc_co_u32_e32 v7, vcc, 0, v7, vcc
	global_load_dword v69, v[6:7], off nt
	v_add_co_u32_e32 v6, vcc, 0x8000, v6
	s_nop 1
	v_addc_co_u32_e32 v7, vcc, 0, v7, vcc
	global_load_dword v70, v[6:7], off nt
	v_add_co_u32_e32 v6, vcc, 0x8000, v6
	s_nop 1
	v_addc_co_u32_e32 v7, vcc, 0, v7, vcc
	global_load_dword v71, v[6:7], off nt
	v_add_co_u32_e32 v6, vcc, 0x8000, v6
	s_nop 1
	v_addc_co_u32_e32 v7, vcc, 0, v7, vcc
	global_load_dword v72, v[6:7], off nt
	v_add_co_u32_e32 v6, vcc, 0x8000, v6
	s_nop 1
	v_addc_co_u32_e32 v7, vcc, 0, v7, vcc
	global_load_dword v73, v[6:7], off nt
	v_add_co_u32_e32 v6, vcc, 0x8000, v6
	s_nop 1
	v_addc_co_u32_e32 v7, vcc, 0, v7, vcc
	global_load_dword v74, v[6:7], off nt
	v_add_co_u32_e32 v6, vcc, 0x8000, v6
	s_nop 1
	v_addc_co_u32_e32 v7, vcc, 0, v7, vcc
	global_load_dword v75, v[6:7], off nt
	v_add_co_u32_e32 v6, vcc, 0x8000, v6
	s_nop 1
	v_addc_co_u32_e32 v7, vcc, 0, v7, vcc
	global_load_dword v76, v[6:7], off nt
	v_add_co_u32_e32 v6, vcc, 0x8000, v6
	s_nop 1
	v_addc_co_u32_e32 v7, vcc, 0, v7, vcc
	global_load_dword v77, v[6:7], off nt
	v_add_co_u32_e32 v6, vcc, 0x8000, v6
	s_nop 1
	v_addc_co_u32_e32 v7, vcc, 0, v7, vcc
	global_load_dword v78, v[6:7], off nt
	v_add_co_u32_e32 v6, vcc, 0x8000, v6
	s_nop 1
	v_addc_co_u32_e32 v7, vcc, 0, v7, vcc
	global_load_dword v79, v[6:7], off nt
	v_add_co_u32_e32 v6, vcc, 0x8000, v6
	s_nop 1
	v_addc_co_u32_e32 v7, vcc, 0, v7, vcc
	global_load_dword v80, v[6:7], off nt
	v_add_co_u32_e32 v6, vcc, 0x8000, v6
	s_nop 1
	v_addc_co_u32_e32 v7, vcc, 0, v7, vcc
	global_load_dword v81, v[6:7], off nt
	v_add_co_u32_e32 v6, vcc, 0x8000, v6
	s_nop 1
	v_addc_co_u32_e32 v7, vcc, 0, v7, vcc
	global_load_dword v82, v[6:7], off nt
	v_add_co_u32_e32 v6, vcc, 0x8000, v6
	s_nop 1
	v_addc_co_u32_e32 v7, vcc, 0, v7, vcc
	global_load_dword v83, v[6:7], off nt
	v_add_co_u32_e32 v6, vcc, 0x8000, v6
	s_nop 1
	v_addc_co_u32_e32 v7, vcc, 0, v7, vcc
	global_load_dword v84, v[6:7], off nt
	v_add_co_u32_e32 v6, vcc, 0x8000, v6
	s_nop 1
	v_addc_co_u32_e32 v7, vcc, 0, v7, vcc
	global_load_dword v85, v[6:7], off nt
	v_add_co_u32_e32 v6, vcc, 0x8000, v6
	s_nop 1
	v_addc_co_u32_e32 v7, vcc, 0, v7, vcc
	global_load_dword v86, v[6:7], off nt
	v_add_co_u32_e32 v6, vcc, 0x8000, v6
	s_nop 1
	v_addc_co_u32_e32 v7, vcc, 0, v7, vcc
	global_load_dword v87, v[6:7], off nt
	v_add_co_u32_e32 v6, vcc, 0x8000, v6
	s_nop 1
	v_addc_co_u32_e32 v7, vcc, 0, v7, vcc
	global_load_dword v88, v[6:7], off nt
	v_add_co_u32_e32 v6, vcc, 0x8000, v6
	s_nop 1
	v_addc_co_u32_e32 v7, vcc, 0, v7, vcc
	global_load_dword v89, v[6:7], off nt
	v_add_co_u32_e32 v6, vcc, 0x8000, v6
	s_nop 1
	v_addc_co_u32_e32 v7, vcc, 0, v7, vcc
	global_load_dword v90, v[6:7], off nt
	v_add_co_u32_e32 v6, vcc, 0x8000, v6
	s_nop 1
	v_addc_co_u32_e32 v7, vcc, 0, v7, vcc
	global_load_dword v91, v[6:7], off nt
	v_add_co_u32_e32 v6, vcc, 0x8000, v6
	s_nop 1
	v_addc_co_u32_e32 v7, vcc, 0, v7, vcc
	global_load_dword v92, v[6:7], off nt
	v_add_co_u32_e32 v6, vcc, 0x8000, v6
	s_nop 1
	v_addc_co_u32_e32 v7, vcc, 0, v7, vcc
	global_load_dword v93, v[6:7], off nt
	v_add_co_u32_e32 v6, vcc, 0x8000, v6
	s_nop 1
	v_addc_co_u32_e32 v7, vcc, 0, v7, vcc
	global_load_dword v94, v[6:7], off nt
	v_add_co_u32_e32 v6, vcc, 0x8000, v6
	s_nop 1
	v_addc_co_u32_e32 v7, vcc, 0, v7, vcc
	global_load_dword v95, v[6:7], off nt
	v_add_co_u32_e32 v6, vcc, 0x8000, v6
	s_nop 1
	v_addc_co_u32_e32 v7, vcc, 0, v7, vcc
	global_load_dword v96, v[6:7], off nt
	v_add_co_u32_e32 v6, vcc, 0x8000, v6
	s_nop 1
	v_addc_co_u32_e32 v7, vcc, 0, v7, vcc
	global_load_dword v97, v[6:7], off nt
	v_add_co_u32_e32 v6, vcc, 0x8000, v6
	s_nop 1
	v_addc_co_u32_e32 v7, vcc, 0, v7, vcc
	global_load_dword v98, v[6:7], off nt
	v_add_co_u32_e32 v6, vcc, 0x8000, v6
	s_nop 1
	v_addc_co_u32_e32 v7, vcc, 0, v7, vcc
	global_load_dword v99, v[6:7], off nt
	v_add_co_u32_e32 v6, vcc, 0x8000, v6
	s_nop 1
	v_addc_co_u32_e32 v7, vcc, 0, v7, vcc
	global_load_dword v100, v[6:7], off nt
	v_add_co_u32_e32 v6, vcc, 0x8000, v6
	s_nop 1
	v_addc_co_u32_e32 v7, vcc, 0, v7, vcc
	global_load_dword v101, v[6:7], off nt
	v_add_co_u32_e32 v6, vcc, 0x8000, v6
	s_nop 1
	v_addc_co_u32_e32 v7, vcc, 0, v7, vcc
	global_load_dword v102, v[6:7], off nt
	v_add_co_u32_e32 v6, vcc, 0x8000, v6
	s_nop 1
	v_addc_co_u32_e32 v7, vcc, 0, v7, vcc
	global_load_dword v103, v[6:7], off nt
	v_add_co_u32_e32 v6, vcc, 0x8000, v6
	s_nop 1
	v_addc_co_u32_e32 v7, vcc, 0, v7, vcc
	global_load_dword v104, v[6:7], off nt
	v_add_co_u32_e32 v6, vcc, 0x8000, v6
	s_nop 1
	v_addc_co_u32_e32 v7, vcc, 0, v7, vcc
	global_load_dword v105, v[6:7], off nt
	v_add_co_u32_e32 v6, vcc, 0x8000, v6
	s_nop 1
	v_addc_co_u32_e32 v7, vcc, 0, v7, vcc
	global_load_dword v106, v[6:7], off nt
	v_add_co_u32_e32 v6, vcc, 0x8000, v6
	s_nop 1
	v_addc_co_u32_e32 v7, vcc, 0, v7, vcc
	global_load_dword v107, v[6:7], off nt
	v_add_co_u32_e32 v6, vcc, 0x8000, v6
	s_nop 1
	v_addc_co_u32_e32 v7, vcc, 0, v7, vcc
	global_load_dword v108, v[6:7], off nt
	v_add_co_u32_e32 v6, vcc, 0x8000, v6
	s_nop 1
	v_addc_co_u32_e32 v7, vcc, 0, v7, vcc
	global_load_dword v109, v[6:7], off nt
	v_add_co_u32_e32 v6, vcc, 0x8000, v6
	s_nop 1
	v_addc_co_u32_e32 v7, vcc, 0, v7, vcc
	global_load_dword v110, v[6:7], off nt
	v_add_co_u32_e32 v6, vcc, 0x8000, v6
	s_nop 1
	v_addc_co_u32_e32 v7, vcc, 0, v7, vcc
	global_load_dword v111, v[6:7], off nt
	v_add_co_u32_e32 v6, vcc, 0x8000, v6
	s_nop 1
	v_addc_co_u32_e32 v7, vcc, 0, v7, vcc
	global_load_dword v112, v[6:7], off nt
	v_add_co_u32_e32 v6, vcc, 0x8000, v6
	s_nop 1
	v_addc_co_u32_e32 v7, vcc, 0, v7, vcc
	global_load_dword v113, v[6:7], off nt
	v_add_co_u32_e32 v6, vcc, 0x8000, v6
	s_nop 1
	v_addc_co_u32_e32 v7, vcc, 0, v7, vcc
	global_load_dword v114, v[6:7], off nt
	v_add_co_u32_e32 v6, vcc, 0x8000, v6
	s_nop 1
	v_addc_co_u32_e32 v7, vcc, 0, v7, vcc
	global_load_dword v115, v[6:7], off nt
	v_add_co_u32_e32 v6, vcc, 0x8000, v6
	s_nop 1
	v_addc_co_u32_e32 v7, vcc, 0, v7, vcc
	global_load_dword v116, v[6:7], off nt
	v_add_co_u32_e32 v6, vcc, 0x8000, v6
	s_nop 1
	v_addc_co_u32_e32 v7, vcc, 0, v7, vcc
	global_load_dword v117, v[6:7], off nt
	v_add_co_u32_e32 v6, vcc, 0x8000, v6
	s_nop 1
	v_addc_co_u32_e32 v7, vcc, 0, v7, vcc
	global_load_dword v118, v[6:7], off nt
	v_add_co_u32_e32 v6, vcc, 0x8000, v6
	s_nop 1
	v_addc_co_u32_e32 v7, vcc, 0, v7, vcc
	global_load_dword v119, v[6:7], off nt
	v_add_co_u32_e32 v6, vcc, 0x8000, v6
	s_nop 1
	v_addc_co_u32_e32 v7, vcc, 0, v7, vcc
	global_load_dword v120, v[6:7], off nt
	v_add_co_u32_e32 v6, vcc, 0x8000, v6
	s_nop 1
	v_addc_co_u32_e32 v7, vcc, 0, v7, vcc
	global_load_dword v121, v[6:7], off nt
	v_add_co_u32_e32 v6, vcc, 0x8000, v6
	s_nop 1
	v_addc_co_u32_e32 v7, vcc, 0, v7, vcc
	global_load_dword v122, v[6:7], off nt
	v_cvt_pk_bf16_f32 v22, v4, v5
	s_waitcnt vmcnt(62)
	global_store_dword v[14:15], v22, off sc1
	v_add_co_u32_e32 v14, vcc, 0x8000, v14
	v_lshlrev_b32_e32 v42, 16, v60
	v_and_b32_e32 v43, 0xffff0000, v60
	v_addc_co_u32_e32 v15, vcc, 0, v15, vcc
	v_pk_fma_f32 v[4:5], v[0:1], v[4:5], v[42:43]
	v_cvt_pk_bf16_f32 v22, v4, v5
	s_waitcnt vmcnt(62)
	global_store_dword v[14:15], v22, off sc1
	v_add_co_u32_e32 v14, vcc, 0x8000, v14
	v_lshlrev_b32_e32 v42, 16, v61
	v_and_b32_e32 v43, 0xffff0000, v61
	v_addc_co_u32_e32 v15, vcc, 0, v15, vcc
	v_pk_fma_f32 v[4:5], v[0:1], v[4:5], v[42:43]
	v_cvt_pk_bf16_f32 v22, v4, v5
	s_waitcnt vmcnt(62)
	global_store_dword v[14:15], v22, off sc1
	v_add_co_u32_e32 v14, vcc, 0x8000, v14
	v_lshlrev_b32_e32 v42, 16, v62
	v_and_b32_e32 v43, 0xffff0000, v62
	v_addc_co_u32_e32 v15, vcc, 0, v15, vcc
	v_pk_fma_f32 v[4:5], v[0:1], v[4:5], v[42:43]
	v_cvt_pk_bf16_f32 v22, v4, v5
	s_waitcnt vmcnt(62)
	global_store_dword v[14:15], v22, off sc1
	v_add_co_u32_e32 v14, vcc, 0x8000, v14
	v_lshlrev_b32_e32 v42, 16, v63
	v_and_b32_e32 v43, 0xffff0000, v63
	v_addc_co_u32_e32 v15, vcc, 0, v15, vcc
	v_pk_fma_f32 v[4:5], v[0:1], v[4:5], v[42:43]
	v_cvt_pk_bf16_f32 v22, v4, v5
	s_waitcnt vmcnt(62)
	global_store_dword v[14:15], v22, off sc1
	v_add_co_u32_e32 v14, vcc, 0x8000, v14
	v_lshlrev_b32_e32 v42, 16, v64
	v_and_b32_e32 v43, 0xffff0000, v64
	v_addc_co_u32_e32 v15, vcc, 0, v15, vcc
	v_pk_fma_f32 v[4:5], v[0:1], v[4:5], v[42:43]
	v_cvt_pk_bf16_f32 v22, v4, v5
	s_waitcnt vmcnt(62)
	global_store_dword v[14:15], v22, off sc1
	v_add_co_u32_e32 v14, vcc, 0x8000, v14
	v_lshlrev_b32_e32 v42, 16, v65
	v_and_b32_e32 v43, 0xffff0000, v65
	v_addc_co_u32_e32 v15, vcc, 0, v15, vcc
	v_pk_fma_f32 v[4:5], v[0:1], v[4:5], v[42:43]
	v_cvt_pk_bf16_f32 v22, v4, v5
	s_waitcnt vmcnt(62)
	global_store_dword v[14:15], v22, off sc1
	v_add_co_u32_e32 v14, vcc, 0x8000, v14
	v_lshlrev_b32_e32 v42, 16, v66
	v_and_b32_e32 v43, 0xffff0000, v66
	v_addc_co_u32_e32 v15, vcc, 0, v15, vcc
	v_pk_fma_f32 v[4:5], v[0:1], v[4:5], v[42:43]
	v_cvt_pk_bf16_f32 v22, v4, v5
	s_waitcnt vmcnt(62)
	global_store_dword v[14:15], v22, off sc1
	v_add_co_u32_e32 v14, vcc, 0x8000, v14
	v_lshlrev_b32_e32 v42, 16, v67
	v_and_b32_e32 v43, 0xffff0000, v67
	v_addc_co_u32_e32 v15, vcc, 0, v15, vcc
	v_pk_fma_f32 v[4:5], v[0:1], v[4:5], v[42:43]
	v_cvt_pk_bf16_f32 v22, v4, v5
	s_waitcnt vmcnt(62)
	global_store_dword v[14:15], v22, off sc1
	v_add_co_u32_e32 v14, vcc, 0x8000, v14
	v_lshlrev_b32_e32 v42, 16, v68
	v_and_b32_e32 v43, 0xffff0000, v68
	v_addc_co_u32_e32 v15, vcc, 0, v15, vcc
	v_pk_fma_f32 v[4:5], v[0:1], v[4:5], v[42:43]
	v_cvt_pk_bf16_f32 v22, v4, v5
	s_waitcnt vmcnt(62)
	global_store_dword v[14:15], v22, off sc1
	v_add_co_u32_e32 v14, vcc, 0x8000, v14
	v_lshlrev_b32_e32 v42, 16, v69
	v_and_b32_e32 v43, 0xffff0000, v69
	v_addc_co_u32_e32 v15, vcc, 0, v15, vcc
	v_pk_fma_f32 v[4:5], v[0:1], v[4:5], v[42:43]
	v_cvt_pk_bf16_f32 v22, v4, v5
	s_waitcnt vmcnt(62)
	global_store_dword v[14:15], v22, off sc1
	v_add_co_u32_e32 v14, vcc, 0x8000, v14
	v_lshlrev_b32_e32 v42, 16, v70
	v_and_b32_e32 v43, 0xffff0000, v70
	v_addc_co_u32_e32 v15, vcc, 0, v15, vcc
	v_pk_fma_f32 v[4:5], v[0:1], v[4:5], v[42:43]
	v_cvt_pk_bf16_f32 v22, v4, v5
	s_waitcnt vmcnt(62)
	global_store_dword v[14:15], v22, off sc1
	v_add_co_u32_e32 v14, vcc, 0x8000, v14
	v_lshlrev_b32_e32 v42, 16, v71
	v_and_b32_e32 v43, 0xffff0000, v71
	v_addc_co_u32_e32 v15, vcc, 0, v15, vcc
	v_pk_fma_f32 v[4:5], v[0:1], v[4:5], v[42:43]
	v_cvt_pk_bf16_f32 v22, v4, v5
	s_waitcnt vmcnt(62)
	global_store_dword v[14:15], v22, off sc1
	v_add_co_u32_e32 v14, vcc, 0x8000, v14
	v_lshlrev_b32_e32 v42, 16, v72
	v_and_b32_e32 v43, 0xffff0000, v72
	v_addc_co_u32_e32 v15, vcc, 0, v15, vcc
	v_pk_fma_f32 v[4:5], v[0:1], v[4:5], v[42:43]
	v_cvt_pk_bf16_f32 v22, v4, v5
	s_waitcnt vmcnt(62)
	global_store_dword v[14:15], v22, off sc1
	v_add_co_u32_e32 v14, vcc, 0x8000, v14
	v_lshlrev_b32_e32 v42, 16, v73
	v_and_b32_e32 v43, 0xffff0000, v73
	v_addc_co_u32_e32 v15, vcc, 0, v15, vcc
	v_pk_fma_f32 v[4:5], v[0:1], v[4:5], v[42:43]
	v_cvt_pk_bf16_f32 v22, v4, v5
	s_waitcnt vmcnt(62)
	global_store_dword v[14:15], v22, off sc1
	v_add_co_u32_e32 v14, vcc, 0x8000, v14
	v_lshlrev_b32_e32 v42, 16, v74
	v_and_b32_e32 v43, 0xffff0000, v74
	v_addc_co_u32_e32 v15, vcc, 0, v15, vcc
	v_pk_fma_f32 v[4:5], v[0:1], v[4:5], v[42:43]
	v_cvt_pk_bf16_f32 v22, v4, v5
	s_waitcnt vmcnt(62)
	global_store_dword v[14:15], v22, off sc1
	v_add_co_u32_e32 v14, vcc, 0x8000, v14
	v_lshlrev_b32_e32 v42, 16, v75
	v_and_b32_e32 v43, 0xffff0000, v75
	v_addc_co_u32_e32 v15, vcc, 0, v15, vcc
	v_pk_fma_f32 v[4:5], v[0:1], v[4:5], v[42:43]
	v_cvt_pk_bf16_f32 v22, v4, v5
	s_waitcnt vmcnt(62)
	global_store_dword v[14:15], v22, off sc1
	v_add_co_u32_e32 v14, vcc, 0x8000, v14
	v_lshlrev_b32_e32 v42, 16, v76
	v_and_b32_e32 v43, 0xffff0000, v76
	v_addc_co_u32_e32 v15, vcc, 0, v15, vcc
	v_pk_fma_f32 v[4:5], v[0:1], v[4:5], v[42:43]
	v_cvt_pk_bf16_f32 v22, v4, v5
	s_waitcnt vmcnt(62)
	global_store_dword v[14:15], v22, off sc1
	v_add_co_u32_e32 v14, vcc, 0x8000, v14
	v_lshlrev_b32_e32 v42, 16, v77
	v_and_b32_e32 v43, 0xffff0000, v77
	v_addc_co_u32_e32 v15, vcc, 0, v15, vcc
	v_pk_fma_f32 v[4:5], v[0:1], v[4:5], v[42:43]
	v_cvt_pk_bf16_f32 v22, v4, v5
	s_waitcnt vmcnt(62)
	global_store_dword v[14:15], v22, off sc1
	v_add_co_u32_e32 v14, vcc, 0x8000, v14
	v_lshlrev_b32_e32 v42, 16, v78
	v_and_b32_e32 v43, 0xffff0000, v78
	v_addc_co_u32_e32 v15, vcc, 0, v15, vcc
	v_pk_fma_f32 v[4:5], v[0:1], v[4:5], v[42:43]
	v_cvt_pk_bf16_f32 v22, v4, v5
	s_waitcnt vmcnt(62)
	global_store_dword v[14:15], v22, off sc1
	v_add_co_u32_e32 v14, vcc, 0x8000, v14
	v_lshlrev_b32_e32 v42, 16, v79
	v_and_b32_e32 v43, 0xffff0000, v79
	v_addc_co_u32_e32 v15, vcc, 0, v15, vcc
	v_pk_fma_f32 v[4:5], v[0:1], v[4:5], v[42:43]
	v_cvt_pk_bf16_f32 v22, v4, v5
	s_waitcnt vmcnt(62)
	global_store_dword v[14:15], v22, off sc1
	v_add_co_u32_e32 v14, vcc, 0x8000, v14
	v_lshlrev_b32_e32 v42, 16, v80
	v_and_b32_e32 v43, 0xffff0000, v80
	v_addc_co_u32_e32 v15, vcc, 0, v15, vcc
	v_pk_fma_f32 v[4:5], v[0:1], v[4:5], v[42:43]
	v_cvt_pk_bf16_f32 v22, v4, v5
	s_waitcnt vmcnt(62)
	global_store_dword v[14:15], v22, off sc1
	v_add_co_u32_e32 v14, vcc, 0x8000, v14
	v_lshlrev_b32_e32 v42, 16, v81
	v_and_b32_e32 v43, 0xffff0000, v81
	v_addc_co_u32_e32 v15, vcc, 0, v15, vcc
	v_pk_fma_f32 v[4:5], v[0:1], v[4:5], v[42:43]
	v_cvt_pk_bf16_f32 v22, v4, v5
	s_waitcnt vmcnt(62)
	global_store_dword v[14:15], v22, off sc1
	v_add_co_u32_e32 v14, vcc, 0x8000, v14
	v_lshlrev_b32_e32 v42, 16, v82
	v_and_b32_e32 v43, 0xffff0000, v82
	v_addc_co_u32_e32 v15, vcc, 0, v15, vcc
	v_pk_fma_f32 v[4:5], v[0:1], v[4:5], v[42:43]
	v_cvt_pk_bf16_f32 v22, v4, v5
	s_waitcnt vmcnt(62)
	global_store_dword v[14:15], v22, off sc1
	v_add_co_u32_e32 v14, vcc, 0x8000, v14
	v_lshlrev_b32_e32 v42, 16, v83
	v_and_b32_e32 v43, 0xffff0000, v83
	v_addc_co_u32_e32 v15, vcc, 0, v15, vcc
	v_pk_fma_f32 v[4:5], v[0:1], v[4:5], v[42:43]
	v_cvt_pk_bf16_f32 v22, v4, v5
	s_waitcnt vmcnt(62)
	global_store_dword v[14:15], v22, off sc1
	v_add_co_u32_e32 v14, vcc, 0x8000, v14
	v_lshlrev_b32_e32 v42, 16, v84
	v_and_b32_e32 v43, 0xffff0000, v84
	v_addc_co_u32_e32 v15, vcc, 0, v15, vcc
	v_pk_fma_f32 v[4:5], v[0:1], v[4:5], v[42:43]
	v_cvt_pk_bf16_f32 v22, v4, v5
	s_waitcnt vmcnt(62)
	global_store_dword v[14:15], v22, off sc1
	v_add_co_u32_e32 v14, vcc, 0x8000, v14
	v_lshlrev_b32_e32 v42, 16, v85
	v_and_b32_e32 v43, 0xffff0000, v85
	v_addc_co_u32_e32 v15, vcc, 0, v15, vcc
	v_pk_fma_f32 v[4:5], v[0:1], v[4:5], v[42:43]
	v_cvt_pk_bf16_f32 v22, v4, v5
	s_waitcnt vmcnt(62)
	global_store_dword v[14:15], v22, off sc1
	v_add_co_u32_e32 v14, vcc, 0x8000, v14
	v_lshlrev_b32_e32 v42, 16, v86
	v_and_b32_e32 v43, 0xffff0000, v86
	v_addc_co_u32_e32 v15, vcc, 0, v15, vcc
	v_pk_fma_f32 v[4:5], v[0:1], v[4:5], v[42:43]
	v_cvt_pk_bf16_f32 v22, v4, v5
	s_waitcnt vmcnt(62)
	global_store_dword v[14:15], v22, off sc1
	v_add_co_u32_e32 v14, vcc, 0x8000, v14
	v_lshlrev_b32_e32 v42, 16, v87
	v_and_b32_e32 v43, 0xffff0000, v87
	v_addc_co_u32_e32 v15, vcc, 0, v15, vcc
	v_pk_fma_f32 v[4:5], v[0:1], v[4:5], v[42:43]
	v_cvt_pk_bf16_f32 v22, v4, v5
	s_waitcnt vmcnt(62)
	global_store_dword v[14:15], v22, off sc1
	v_add_co_u32_e32 v14, vcc, 0x8000, v14
	v_lshlrev_b32_e32 v42, 16, v88
	v_and_b32_e32 v43, 0xffff0000, v88
	v_addc_co_u32_e32 v15, vcc, 0, v15, vcc
	v_pk_fma_f32 v[4:5], v[0:1], v[4:5], v[42:43]
	v_cvt_pk_bf16_f32 v22, v4, v5
	s_waitcnt vmcnt(62)
	global_store_dword v[14:15], v22, off sc1
	v_add_co_u32_e32 v14, vcc, 0x8000, v14
	v_lshlrev_b32_e32 v42, 16, v89
	v_and_b32_e32 v43, 0xffff0000, v89
	v_addc_co_u32_e32 v15, vcc, 0, v15, vcc
	v_pk_fma_f32 v[4:5], v[0:1], v[4:5], v[42:43]
	v_cvt_pk_bf16_f32 v22, v4, v5
	s_waitcnt vmcnt(62)
	global_store_dword v[14:15], v22, off sc1
	v_add_co_u32_e32 v14, vcc, 0x8000, v14
	v_lshlrev_b32_e32 v42, 16, v90
	v_and_b32_e32 v43, 0xffff0000, v90
	v_addc_co_u32_e32 v15, vcc, 0, v15, vcc
	v_pk_fma_f32 v[4:5], v[0:1], v[4:5], v[42:43]
	v_cvt_pk_bf16_f32 v22, v4, v5
	s_waitcnt vmcnt(62)
	global_store_dword v[14:15], v22, off sc1
	v_add_co_u32_e32 v14, vcc, 0x8000, v14
	v_lshlrev_b32_e32 v42, 16, v91
	v_and_b32_e32 v43, 0xffff0000, v91
	v_addc_co_u32_e32 v15, vcc, 0, v15, vcc
	v_pk_fma_f32 v[4:5], v[0:1], v[4:5], v[42:43]
	v_cvt_pk_bf16_f32 v22, v4, v5
	s_waitcnt vmcnt(62)
	global_store_dword v[14:15], v22, off sc1
	v_add_co_u32_e32 v14, vcc, 0x8000, v14
	v_lshlrev_b32_e32 v42, 16, v92
	v_and_b32_e32 v43, 0xffff0000, v92
	v_addc_co_u32_e32 v15, vcc, 0, v15, vcc
	v_pk_fma_f32 v[4:5], v[0:1], v[4:5], v[42:43]
	v_cvt_pk_bf16_f32 v22, v4, v5
	s_waitcnt vmcnt(62)
	global_store_dword v[14:15], v22, off sc1
	v_add_co_u32_e32 v14, vcc, 0x8000, v14
	v_lshlrev_b32_e32 v42, 16, v93
	v_and_b32_e32 v43, 0xffff0000, v93
	v_addc_co_u32_e32 v15, vcc, 0, v15, vcc
	v_pk_fma_f32 v[4:5], v[0:1], v[4:5], v[42:43]
	v_cvt_pk_bf16_f32 v22, v4, v5
	s_waitcnt vmcnt(62)
	global_store_dword v[14:15], v22, off sc1
	v_add_co_u32_e32 v14, vcc, 0x8000, v14
	v_lshlrev_b32_e32 v42, 16, v94
	v_and_b32_e32 v43, 0xffff0000, v94
	v_addc_co_u32_e32 v15, vcc, 0, v15, vcc
	v_pk_fma_f32 v[4:5], v[0:1], v[4:5], v[42:43]
	v_cvt_pk_bf16_f32 v22, v4, v5
	s_waitcnt vmcnt(62)
	global_store_dword v[14:15], v22, off sc1
	v_add_co_u32_e32 v14, vcc, 0x8000, v14
	v_lshlrev_b32_e32 v42, 16, v95
	v_and_b32_e32 v43, 0xffff0000, v95
	v_addc_co_u32_e32 v15, vcc, 0, v15, vcc
	v_pk_fma_f32 v[4:5], v[0:1], v[4:5], v[42:43]
	v_cvt_pk_bf16_f32 v22, v4, v5
	s_waitcnt vmcnt(62)
	global_store_dword v[14:15], v22, off sc1
	v_add_co_u32_e32 v14, vcc, 0x8000, v14
	v_lshlrev_b32_e32 v42, 16, v96
	v_and_b32_e32 v43, 0xffff0000, v96
	v_addc_co_u32_e32 v15, vcc, 0, v15, vcc
	v_pk_fma_f32 v[4:5], v[0:1], v[4:5], v[42:43]
	v_cvt_pk_bf16_f32 v22, v4, v5
	s_waitcnt vmcnt(62)
	global_store_dword v[14:15], v22, off sc1
	v_add_co_u32_e32 v14, vcc, 0x8000, v14
	v_lshlrev_b32_e32 v42, 16, v97
	v_and_b32_e32 v43, 0xffff0000, v97
	v_addc_co_u32_e32 v15, vcc, 0, v15, vcc
	v_pk_fma_f32 v[4:5], v[0:1], v[4:5], v[42:43]
	v_cvt_pk_bf16_f32 v22, v4, v5
	s_waitcnt vmcnt(62)
	global_store_dword v[14:15], v22, off sc1
	v_add_co_u32_e32 v14, vcc, 0x8000, v14
	v_lshlrev_b32_e32 v42, 16, v98
	v_and_b32_e32 v43, 0xffff0000, v98
	v_addc_co_u32_e32 v15, vcc, 0, v15, vcc
	v_pk_fma_f32 v[4:5], v[0:1], v[4:5], v[42:43]
	v_cvt_pk_bf16_f32 v22, v4, v5
	s_waitcnt vmcnt(62)
	global_store_dword v[14:15], v22, off sc1
	v_add_co_u32_e32 v14, vcc, 0x8000, v14
	v_lshlrev_b32_e32 v42, 16, v99
	v_and_b32_e32 v43, 0xffff0000, v99
	v_addc_co_u32_e32 v15, vcc, 0, v15, vcc
	v_pk_fma_f32 v[4:5], v[0:1], v[4:5], v[42:43]
	v_cvt_pk_bf16_f32 v22, v4, v5
	s_waitcnt vmcnt(62)
	global_store_dword v[14:15], v22, off sc1
	v_add_co_u32_e32 v14, vcc, 0x8000, v14
	v_lshlrev_b32_e32 v42, 16, v100
	v_and_b32_e32 v43, 0xffff0000, v100
	v_addc_co_u32_e32 v15, vcc, 0, v15, vcc
	v_pk_fma_f32 v[4:5], v[0:1], v[4:5], v[42:43]
	v_cvt_pk_bf16_f32 v22, v4, v5
	s_waitcnt vmcnt(62)
	global_store_dword v[14:15], v22, off sc1
	v_add_co_u32_e32 v14, vcc, 0x8000, v14
	v_lshlrev_b32_e32 v42, 16, v101
	v_and_b32_e32 v43, 0xffff0000, v101
	v_addc_co_u32_e32 v15, vcc, 0, v15, vcc
	v_pk_fma_f32 v[4:5], v[0:1], v[4:5], v[42:43]
	v_cvt_pk_bf16_f32 v22, v4, v5
	s_waitcnt vmcnt(62)
	global_store_dword v[14:15], v22, off sc1
	v_add_co_u32_e32 v14, vcc, 0x8000, v14
	v_lshlrev_b32_e32 v42, 16, v102
	v_and_b32_e32 v43, 0xffff0000, v102
	v_addc_co_u32_e32 v15, vcc, 0, v15, vcc
	v_pk_fma_f32 v[4:5], v[0:1], v[4:5], v[42:43]
	v_cvt_pk_bf16_f32 v22, v4, v5
	s_waitcnt vmcnt(62)
	global_store_dword v[14:15], v22, off sc1
	v_add_co_u32_e32 v14, vcc, 0x8000, v14
	v_lshlrev_b32_e32 v42, 16, v103
	v_and_b32_e32 v43, 0xffff0000, v103
	v_addc_co_u32_e32 v15, vcc, 0, v15, vcc
	v_pk_fma_f32 v[4:5], v[0:1], v[4:5], v[42:43]
	v_cvt_pk_bf16_f32 v22, v4, v5
	s_waitcnt vmcnt(62)
	global_store_dword v[14:15], v22, off sc1
	v_add_co_u32_e32 v14, vcc, 0x8000, v14
	v_lshlrev_b32_e32 v42, 16, v104
	v_and_b32_e32 v43, 0xffff0000, v104
	v_addc_co_u32_e32 v15, vcc, 0, v15, vcc
	v_pk_fma_f32 v[4:5], v[0:1], v[4:5], v[42:43]
	v_cvt_pk_bf16_f32 v22, v4, v5
	s_waitcnt vmcnt(62)
	global_store_dword v[14:15], v22, off sc1
	v_add_co_u32_e32 v14, vcc, 0x8000, v14
	v_lshlrev_b32_e32 v42, 16, v105
	v_and_b32_e32 v43, 0xffff0000, v105
	v_addc_co_u32_e32 v15, vcc, 0, v15, vcc
	v_pk_fma_f32 v[4:5], v[0:1], v[4:5], v[42:43]
	v_cvt_pk_bf16_f32 v22, v4, v5
	s_waitcnt vmcnt(62)
	global_store_dword v[14:15], v22, off sc1
	v_add_co_u32_e32 v14, vcc, 0x8000, v14
	v_lshlrev_b32_e32 v42, 16, v106
	v_and_b32_e32 v43, 0xffff0000, v106
	v_addc_co_u32_e32 v15, vcc, 0, v15, vcc
	v_pk_fma_f32 v[4:5], v[0:1], v[4:5], v[42:43]
	v_cvt_pk_bf16_f32 v22, v4, v5
	s_waitcnt vmcnt(62)
	global_store_dword v[14:15], v22, off sc1
	v_add_co_u32_e32 v14, vcc, 0x8000, v14
	v_lshlrev_b32_e32 v42, 16, v107
	v_and_b32_e32 v43, 0xffff0000, v107
	v_addc_co_u32_e32 v15, vcc, 0, v15, vcc
	v_pk_fma_f32 v[4:5], v[0:1], v[4:5], v[42:43]
	v_cvt_pk_bf16_f32 v22, v4, v5
	s_waitcnt vmcnt(62)
	global_store_dword v[14:15], v22, off sc1
	v_add_co_u32_e32 v14, vcc, 0x8000, v14
	v_lshlrev_b32_e32 v42, 16, v108
	v_and_b32_e32 v43, 0xffff0000, v108
	v_addc_co_u32_e32 v15, vcc, 0, v15, vcc
	v_pk_fma_f32 v[4:5], v[0:1], v[4:5], v[42:43]
	v_cvt_pk_bf16_f32 v22, v4, v5
	s_waitcnt vmcnt(62)
	global_store_dword v[14:15], v22, off sc1
	v_add_co_u32_e32 v14, vcc, 0x8000, v14
	v_lshlrev_b32_e32 v42, 16, v109
	v_and_b32_e32 v43, 0xffff0000, v109
	v_addc_co_u32_e32 v15, vcc, 0, v15, vcc
	v_pk_fma_f32 v[4:5], v[0:1], v[4:5], v[42:43]
	v_cvt_pk_bf16_f32 v22, v4, v5
	s_waitcnt vmcnt(62)
	global_store_dword v[14:15], v22, off sc1
	v_add_co_u32_e32 v14, vcc, 0x8000, v14
	v_lshlrev_b32_e32 v42, 16, v110
	v_and_b32_e32 v43, 0xffff0000, v110
	v_addc_co_u32_e32 v15, vcc, 0, v15, vcc
	v_pk_fma_f32 v[4:5], v[0:1], v[4:5], v[42:43]
	v_cvt_pk_bf16_f32 v22, v4, v5
	s_waitcnt vmcnt(62)
	global_store_dword v[14:15], v22, off sc1
	v_add_co_u32_e32 v14, vcc, 0x8000, v14
	v_lshlrev_b32_e32 v42, 16, v111
	v_and_b32_e32 v43, 0xffff0000, v111
	v_addc_co_u32_e32 v15, vcc, 0, v15, vcc
	v_pk_fma_f32 v[4:5], v[0:1], v[4:5], v[42:43]
	v_cvt_pk_bf16_f32 v22, v4, v5
	s_waitcnt vmcnt(62)
	global_store_dword v[14:15], v22, off sc1
	v_add_co_u32_e32 v14, vcc, 0x8000, v14
	v_lshlrev_b32_e32 v42, 16, v112
	v_and_b32_e32 v43, 0xffff0000, v112
	v_addc_co_u32_e32 v15, vcc, 0, v15, vcc
	v_pk_fma_f32 v[4:5], v[0:1], v[4:5], v[42:43]
	v_cvt_pk_bf16_f32 v22, v4, v5
	s_waitcnt vmcnt(62)
	global_store_dword v[14:15], v22, off sc1
	v_add_co_u32_e32 v14, vcc, 0x8000, v14
	v_lshlrev_b32_e32 v42, 16, v113
	v_and_b32_e32 v43, 0xffff0000, v113
	v_addc_co_u32_e32 v15, vcc, 0, v15, vcc
	v_pk_fma_f32 v[4:5], v[0:1], v[4:5], v[42:43]
	v_cvt_pk_bf16_f32 v22, v4, v5
	s_waitcnt vmcnt(62)
	global_store_dword v[14:15], v22, off sc1
	v_add_co_u32_e32 v14, vcc, 0x8000, v14
	v_lshlrev_b32_e32 v42, 16, v114
	v_and_b32_e32 v43, 0xffff0000, v114
	v_addc_co_u32_e32 v15, vcc, 0, v15, vcc
	v_pk_fma_f32 v[4:5], v[0:1], v[4:5], v[42:43]
	v_cvt_pk_bf16_f32 v22, v4, v5
	s_waitcnt vmcnt(62)
	global_store_dword v[14:15], v22, off sc1
	v_add_co_u32_e32 v14, vcc, 0x8000, v14
	v_lshlrev_b32_e32 v42, 16, v115
	v_and_b32_e32 v43, 0xffff0000, v115
	v_addc_co_u32_e32 v15, vcc, 0, v15, vcc
	v_pk_fma_f32 v[4:5], v[0:1], v[4:5], v[42:43]
	v_cvt_pk_bf16_f32 v22, v4, v5
	s_waitcnt vmcnt(62)
	global_store_dword v[14:15], v22, off sc1
	v_add_co_u32_e32 v14, vcc, 0x8000, v14
	v_lshlrev_b32_e32 v42, 16, v116
	v_and_b32_e32 v43, 0xffff0000, v116
	v_addc_co_u32_e32 v15, vcc, 0, v15, vcc
	v_pk_fma_f32 v[4:5], v[0:1], v[4:5], v[42:43]
	v_cvt_pk_bf16_f32 v22, v4, v5
	s_waitcnt vmcnt(62)
	global_store_dword v[14:15], v22, off sc1
	v_add_co_u32_e32 v14, vcc, 0x8000, v14
	v_lshlrev_b32_e32 v42, 16, v117
	v_and_b32_e32 v43, 0xffff0000, v117
	v_addc_co_u32_e32 v15, vcc, 0, v15, vcc
	v_pk_fma_f32 v[4:5], v[0:1], v[4:5], v[42:43]
	v_cvt_pk_bf16_f32 v22, v4, v5
	s_waitcnt vmcnt(62)
	global_store_dword v[14:15], v22, off sc1
	v_add_co_u32_e32 v14, vcc, 0x8000, v14
	v_lshlrev_b32_e32 v42, 16, v118
	v_and_b32_e32 v43, 0xffff0000, v118
	v_addc_co_u32_e32 v15, vcc, 0, v15, vcc
	v_pk_fma_f32 v[4:5], v[0:1], v[4:5], v[42:43]
	v_cvt_pk_bf16_f32 v22, v4, v5
	s_waitcnt vmcnt(62)
	global_store_dword v[14:15], v22, off sc1
	v_add_co_u32_e32 v14, vcc, 0x8000, v14
	v_lshlrev_b32_e32 v42, 16, v119
	v_and_b32_e32 v43, 0xffff0000, v119
	v_addc_co_u32_e32 v15, vcc, 0, v15, vcc
	v_pk_fma_f32 v[4:5], v[0:1], v[4:5], v[42:43]
	v_cvt_pk_bf16_f32 v22, v4, v5
	s_waitcnt vmcnt(62)
	global_store_dword v[14:15], v22, off sc1
	v_add_co_u32_e32 v14, vcc, 0x8000, v14
	v_lshlrev_b32_e32 v42, 16, v120
	v_and_b32_e32 v43, 0xffff0000, v120
	v_addc_co_u32_e32 v15, vcc, 0, v15, vcc
	v_pk_fma_f32 v[4:5], v[0:1], v[4:5], v[42:43]
	v_cvt_pk_bf16_f32 v22, v4, v5
	s_waitcnt vmcnt(62)
	global_store_dword v[14:15], v22, off sc1
	v_add_co_u32_e32 v14, vcc, 0x8000, v14
	v_lshlrev_b32_e32 v42, 16, v121
	v_and_b32_e32 v43, 0xffff0000, v121
	v_addc_co_u32_e32 v15, vcc, 0, v15, vcc
	v_pk_fma_f32 v[4:5], v[0:1], v[4:5], v[42:43]
	v_cvt_pk_bf16_f32 v22, v4, v5
	s_waitcnt vmcnt(62)
	global_store_dword v[14:15], v22, off sc1
	v_add_co_u32_e32 v14, vcc, 0x8000, v14
	v_lshlrev_b32_e32 v42, 16, v122
	v_and_b32_e32 v43, 0xffff0000, v122
	v_addc_co_u32_e32 v15, vcc, 0, v15, vcc
	v_pk_fma_f32 v[4:5], v[0:1], v[4:5], v[42:43]
	v_cvt_pk_bf16_f32 v22, v4, v5
	global_store_dword v[14:15], v22, off sc1
	v_add_u32_e32 v8, s3, v8
	v_cmp_lt_i32_e32 vcc, s28, v8
	s_or_b64 s[8:9], vcc, s[8:9]
	v_add_u32_e32 v9, s12, v9
	s_andn2_b64 exec, exec, s[8:9]
	s_cbranch_execnz .LBB0_476
